# retention loop: packed f32 multiplies beside the MFMAs split into scalar pairs (state and output decay)
# baseline (speedup 1.0000x reference)
; #define LAS __attribute__((address_space(3)))
; #define LDS_BAR() do { asm volatile("s_waitcnt lgkmcnt(0)" ::: "memory"); __builtin_amdgcn_s_barrier(); asm volatile("" ::: "memory"); } while (0)
; #define SB0 __builtin_amdgcn_sched_barrier(0)
; #define RET_STAGE(Kd, Vd) do { _Pragma("unroll") for (int uu = 0; uu < 4; ++uu) { const int c8 = lc8 + 8 * uu; *(LAS u32x4*)(Ql + ls * 264 + 8 * c8) = pq[uu]; *(LAS u32x4*)((Kd) + ls * 264 + 8 * c8) = pkv[uu]; } \
;         _Pragma("unroll") for (int uu = 0; uu < 2; ++uu) { const int c8 = lc8 + 8 * uu; *(LAS u32x4*)((Vd) + ls * 136 + 8 * c8) = pv[uu]; } } while (0)
; #define SB0 __builtin_amdgcn_sched_barrier(0)
; #define RD_LOAD(m_) do { _Pragma("unroll") for (int ks = 0; ks < 2; ++ks) TR_FRAG(kf[(m_) % 3][ks], Kl, 264, 16 * (m_), ks); } while (0)
; __device__ __forceinline__ void ret_unit(LAS unsigned char* lds, bf16_t* QKV, float* gn, int b, int h, int vs, bool commit, const float* s00p, const float* ss3, bool skel = false) {
;     ...
;         for (int n = 0; n < 4; ++n) oacc[n] = oacc[n] * cd;
;         }
;         LDS_BAR();
;         if (c + 1 < 32) { RET_STAGE(Kn, Vn); if (c + 2 < 32) RET_LOAD(c + 2); }
;         if (!skel) {
;         bf16x8 vfrag[2];
;         { bf16x8 pf[2][4];
; #pragma unroll
;           for (int ks = 0; ks < 2; ++ks) { TR_FRAG(vfrag[ks], Vl, 136, 16 * w, ks);
; #pragma unroll
;               for (int n = 0; n < 4; ++n) pf[ks][n] = *(const LAS bf16x8*)(Pl + (16 * n + fr) * 72 + 32 * ks + 8 * fq); }
;           bf16x8 kf[3][2];
;     ...
;           RD_LOAD(0); RD_LOAD(1); SB0;
; #pragma unroll
;           for (int ks = 0; ks < 2; ++ks)
; #pragma unroll
;               for (int n = 0; n < 4; ++n) oacc[n] = __builtin_amdgcn_mfma_f32_16x16x32_bf16(vfrag[ks], pf[ks][n], oacc[n], 0, 0, 0);
;           SB0;
; #pragma unroll
;           for (int m = 0; m < 16; ++m) { if (m + 2 < 16) RD_LOAD(m + 2);
;               state[m] = state[m] * cd; SB0;
; #pragma unroll
;               for (int ks = 0; ks < 2; ++ks) state[m] = __builtin_amdgcn_mfma_f32_16x16x32_bf16(kf[m % 3][ks], vfrag[ks], state[m], 0, 0, 0);
;               SB0; }
.LBB0_1139:
	s_mulk_i32 s65, 0x4400
	v_mov_b32_e32 v151, v150
	v_add_u32_e32 v122, s65, v200
	v_mul_f32_e32 v126, v150, v118
	v_mul_f32_e32 v127, v151, v119
	v_mul_f32_e32 v124, v152, v116
	v_mul_f32_e32 v125, v153, v117
	ds_read_b64_tr_b16 v[116:117], v122
	ds_read_b64_tr_b16 v[118:119], v122 offset:1088
	ds_read_b128 v[206:209], v205
	ds_read_b128 v[210:213], v205 offset:2304
	ds_read_b128 v[214:217], v205 offset:4608
	ds_read_b128 v[218:221], v205 offset:6912
	ds_read_b64_tr_b16 v[120:121], v122 offset:8704
	ds_read_b64_tr_b16 v[122:123], v122 offset:9792
	ds_read_b128 v[222:225], v205 offset:64
	ds_read_b128 v[226:229], v205 offset:2368
	ds_read_b128 v[230:233], v205 offset:4672
	ds_read_b128 v[234:237], v205 offset:6976
	v_add3_u32 v149, s64, v165, v199
	v_add3_u32 v252, s64, v199, v165
	ds_read_b64_tr_b16 v[238:239], v149
	ds_read_b64_tr_b16 v[240:241], v149 offset:2112
	ds_read_b64_tr_b16 v[242:243], v149 offset:16896
	ds_read_b64_tr_b16 v[244:245], v149 offset:19008
	ds_read_b64_tr_b16 v[246:247], v252 offset:32
	ds_read_b64_tr_b16 v[248:249], v252 offset:2144
	ds_read_b64_tr_b16 v[250:251], v252 offset:16928
	ds_read_b64_tr_b16 v[252:253], v252 offset:19040
	v_mul_f32_e32 v114, v150, v114
	v_mul_f32_e32 v115, v151, v115
	v_mul_f32_e32 v112, v152, v112
	v_mul_f32_e32 v113, v153, v113
	v_mul_f32_e32 v110, v150, v110
	v_mul_f32_e32 v111, v151, v111
	v_mul_f32_e32 v108, v152, v108
	v_mul_f32_e32 v109, v153, v109
	v_mul_f32_e32 v106, v150, v106
	v_mul_f32_e32 v107, v151, v107
	v_mul_f32_e32 v104, v152, v104
	v_mul_f32_e32 v105, v153, v105
	s_waitcnt lgkmcnt(14)
	v_mfma_f32_16x16x32_bf16 v[124:127], v[116:119], v[206:209], v[124:127]
	v_mfma_f32_16x16x32_bf16 v[112:115], v[116:119], v[210:213], v[112:115]
	v_mfma_f32_16x16x32_bf16 v[108:111], v[116:119], v[214:217], v[108:111]
	v_mfma_f32_16x16x32_bf16 v[104:107], v[116:119], v[218:221], v[104:107]
	s_waitcnt lgkmcnt(11)
	v_mfma_f32_16x16x32_bf16 v[124:127], v[120:123], v[222:225], v[124:127]
	s_waitcnt lgkmcnt(10)
	v_mfma_f32_16x16x32_bf16 v[112:115], v[120:123], v[226:229], v[112:115]
	s_waitcnt lgkmcnt(9)
	v_mfma_f32_16x16x32_bf16 v[108:111], v[120:123], v[230:233], v[108:111]
	s_waitcnt lgkmcnt(8)
	v_mfma_f32_16x16x32_bf16 v[104:107], v[120:123], v[234:237], v[104:107]
	ds_read_b64_tr_b16 v[206:207], v149 offset:64
	ds_read_b64_tr_b16 v[208:209], v149 offset:2176
	ds_read_b64_tr_b16 v[210:211], v149 offset:16960
	ds_read_b64_tr_b16 v[212:213], v149 offset:19072
	v_mul_f32_e32 v62, v150, v62
	v_mul_f32_e32 v63, v151, v63
	v_mul_f32_e32 v60, v152, v60
	v_mul_f32_e32 v61, v153, v61
	s_waitcnt lgkmcnt(10)
	s_nop 0
	v_mfma_f32_16x16x32_bf16 v[60:63], v[238:241], v[116:119], v[60:63]
	s_waitcnt lgkmcnt(8)
	v_mfma_f32_16x16x32_bf16 v[60:63], v[242:245], v[120:123], v[60:63]
	ds_read_b64_tr_b16 v[214:215], v149 offset:96
	ds_read_b64_tr_b16 v[216:217], v149 offset:2208
	ds_read_b64_tr_b16 v[218:219], v149 offset:16992
	ds_read_b64_tr_b16 v[220:221], v149 offset:19104
	v_mul_f32_e32 v58, v150, v58
	v_mul_f32_e32 v59, v151, v59
	v_mul_f32_e32 v56, v152, v56
	v_mul_f32_e32 v57, v153, v57
	s_waitcnt lgkmcnt(10)
	s_nop 0
	v_mfma_f32_16x16x32_bf16 v[56:59], v[246:249], v[116:119], v[56:59]
	s_waitcnt lgkmcnt(8)
	v_mfma_f32_16x16x32_bf16 v[56:59], v[250:253], v[120:123], v[56:59]
	ds_read_b64_tr_b16 v[222:223], v149 offset:128
	ds_read_b64_tr_b16 v[224:225], v149 offset:2240
	ds_read_b64_tr_b16 v[226:227], v149 offset:17024
	ds_read_b64_tr_b16 v[228:229], v149 offset:19136
	v_mul_f32_e32 v54, v150, v54
	v_mul_f32_e32 v55, v151, v55
	v_mul_f32_e32 v52, v152, v52
	v_mul_f32_e32 v53, v153, v53
	s_waitcnt lgkmcnt(10)
	s_nop 0
	v_mfma_f32_16x16x32_bf16 v[52:55], v[206:209], v[116:119], v[52:55]
	s_waitcnt lgkmcnt(8)
	v_mfma_f32_16x16x32_bf16 v[52:55], v[210:213], v[120:123], v[52:55]
	ds_read_b64_tr_b16 v[206:207], v149 offset:160
	ds_read_b64_tr_b16 v[208:209], v149 offset:2272
	ds_read_b64_tr_b16 v[210:211], v149 offset:17056
	ds_read_b64_tr_b16 v[212:213], v149 offset:19168
	v_mul_f32_e32 v50, v150, v50
	v_mul_f32_e32 v51, v151, v51
	v_mul_f32_e32 v48, v152, v48
	v_mul_f32_e32 v49, v153, v49
	s_waitcnt lgkmcnt(10)
	s_nop 0
	v_mfma_f32_16x16x32_bf16 v[48:51], v[214:217], v[116:119], v[48:51]
	s_waitcnt lgkmcnt(8)
	v_mfma_f32_16x16x32_bf16 v[48:51], v[218:221], v[120:123], v[48:51]
	ds_read_b64_tr_b16 v[214:215], v149 offset:192
	ds_read_b64_tr_b16 v[216:217], v149 offset:2304
	ds_read_b64_tr_b16 v[218:219], v149 offset:17088
	ds_read_b64_tr_b16 v[220:221], v149 offset:19200
	v_mul_f32_e32 v46, v150, v46
	v_mul_f32_e32 v47, v151, v47
	v_mul_f32_e32 v44, v152, v44
	v_mul_f32_e32 v45, v153, v45
	s_waitcnt lgkmcnt(10)
	s_nop 0
	v_mfma_f32_16x16x32_bf16 v[44:47], v[222:225], v[116:119], v[44:47]
	s_waitcnt lgkmcnt(8)
	v_mfma_f32_16x16x32_bf16 v[44:47], v[226:229], v[120:123], v[44:47]
	ds_read_b64_tr_b16 v[222:223], v149 offset:224
	ds_read_b64_tr_b16 v[224:225], v149 offset:2336
	ds_read_b64_tr_b16 v[226:227], v149 offset:17120
	ds_read_b64_tr_b16 v[228:229], v149 offset:19232
	v_mul_f32_e32 v42, v150, v42
	v_mul_f32_e32 v43, v151, v43
	v_mul_f32_e32 v40, v152, v40
	v_mul_f32_e32 v41, v153, v41
	s_waitcnt lgkmcnt(10)
	s_nop 0
	v_mfma_f32_16x16x32_bf16 v[40:43], v[206:209], v[116:119], v[40:43]
	s_waitcnt lgkmcnt(8)
	v_mfma_f32_16x16x32_bf16 v[40:43], v[210:213], v[120:123], v[40:43]
	ds_read_b64_tr_b16 v[206:207], v149 offset:256
	ds_read_b64_tr_b16 v[208:209], v149 offset:2368
	ds_read_b64_tr_b16 v[210:211], v149 offset:17152
	ds_read_b64_tr_b16 v[212:213], v149 offset:19264
	v_mul_f32_e32 v38, v150, v38
	v_mul_f32_e32 v39, v151, v39
	v_mul_f32_e32 v36, v152, v36
	v_mul_f32_e32 v37, v153, v37
	s_waitcnt lgkmcnt(10)
; #define SB0 __builtin_amdgcn_sched_barrier(0)
; #define SB0 __builtin_amdgcn_sched_barrier(0)
; #define RD_LOAD(m_) do { _Pragma("unroll") for (int ks = 0; ks < 2; ++ks) TR_FRAG(kf[(m_) % 3][ks], Kl, 264, 16 * (m_), ks); } while (0)
; __device__ __forceinline__ void ret_unit(LAS unsigned char* lds, bf16_t* QKV, float* gn, int b, int h, int vs, bool commit, const float* s00p, const float* ss3, bool skel = false) {
;     ...
; #pragma unroll
;           for (int m = 0; m < 16; ++m) { if (m + 2 < 16) RD_LOAD(m + 2);
;               state[m] = state[m] * cd; SB0;
; #pragma unroll
;               for (int ks = 0; ks < 2; ++ks) state[m] = __builtin_amdgcn_mfma_f32_16x16x32_bf16(kf[m % 3][ks], vfrag[ks], state[m], 0, 0, 0);
;               SB0; }
	s_nop 0
	v_mfma_f32_16x16x32_bf16 v[36:39], v[214:217], v[116:119], v[36:39]
	s_waitcnt lgkmcnt(8)
	v_mfma_f32_16x16x32_bf16 v[36:39], v[218:221], v[120:123], v[36:39]
	ds_read_b64_tr_b16 v[214:215], v149 offset:288
	ds_read_b64_tr_b16 v[216:217], v149 offset:2400
	ds_read_b64_tr_b16 v[218:219], v149 offset:17184
	ds_read_b64_tr_b16 v[220:221], v149 offset:19296
	v_mul_f32_e32 v34, v150, v34
	v_mul_f32_e32 v35, v151, v35
	v_mul_f32_e32 v32, v152, v32
	v_mul_f32_e32 v33, v153, v33
	s_waitcnt lgkmcnt(10)
	s_nop 0
	v_mfma_f32_16x16x32_bf16 v[32:35], v[222:225], v[116:119], v[32:35]
	s_waitcnt lgkmcnt(8)
	v_mfma_f32_16x16x32_bf16 v[32:35], v[226:229], v[120:123], v[32:35]
	ds_read_b64_tr_b16 v[222:223], v149 offset:320
	ds_read_b64_tr_b16 v[224:225], v149 offset:2432
	ds_read_b64_tr_b16 v[226:227], v149 offset:17216
	ds_read_b64_tr_b16 v[228:229], v149 offset:19328
	v_mul_f32_e32 v30, v150, v30
	v_mul_f32_e32 v31, v151, v31
	v_mul_f32_e32 v28, v152, v28
	v_mul_f32_e32 v29, v153, v29
	s_waitcnt lgkmcnt(10)
	s_nop 0
	v_mfma_f32_16x16x32_bf16 v[28:31], v[206:209], v[116:119], v[28:31]
	s_waitcnt lgkmcnt(8)
	v_mfma_f32_16x16x32_bf16 v[28:31], v[210:213], v[120:123], v[28:31]
	ds_read_b64_tr_b16 v[206:207], v149 offset:352
	ds_read_b64_tr_b16 v[208:209], v149 offset:2464
	ds_read_b64_tr_b16 v[210:211], v149 offset:17248
	ds_read_b64_tr_b16 v[212:213], v149 offset:19360
	v_mul_f32_e32 v26, v150, v26
	v_mul_f32_e32 v27, v151, v27
	v_mul_f32_e32 v24, v152, v24
	v_mul_f32_e32 v25, v153, v25
	s_waitcnt lgkmcnt(10)
	s_nop 0
	v_mfma_f32_16x16x32_bf16 v[24:27], v[214:217], v[116:119], v[24:27]
	s_waitcnt lgkmcnt(8)
	v_mfma_f32_16x16x32_bf16 v[24:27], v[218:221], v[120:123], v[24:27]
	ds_read_b64_tr_b16 v[214:215], v149 offset:384
	ds_read_b64_tr_b16 v[216:217], v149 offset:2496
	ds_read_b64_tr_b16 v[218:219], v149 offset:17280
	ds_read_b64_tr_b16 v[220:221], v149 offset:19392
	v_mul_f32_e32 v22, v150, v22
	v_mul_f32_e32 v23, v151, v23
	v_mul_f32_e32 v20, v152, v20
	v_mul_f32_e32 v21, v153, v21
	s_waitcnt lgkmcnt(10)
	s_nop 0
	v_mfma_f32_16x16x32_bf16 v[20:23], v[222:225], v[116:119], v[20:23]
	s_waitcnt lgkmcnt(8)
	v_mfma_f32_16x16x32_bf16 v[20:23], v[226:229], v[120:123], v[20:23]
	ds_read_b64_tr_b16 v[222:223], v149 offset:416
	ds_read_b64_tr_b16 v[224:225], v149 offset:2528
	ds_read_b64_tr_b16 v[226:227], v149 offset:17312
	ds_read_b64_tr_b16 v[228:229], v149 offset:19424
	v_mul_f32_e32 v18, v150, v18
	v_mul_f32_e32 v19, v151, v19
	v_mul_f32_e32 v16, v152, v16
	v_mul_f32_e32 v17, v153, v17
	s_waitcnt lgkmcnt(10)
	s_nop 0
	v_mfma_f32_16x16x32_bf16 v[16:19], v[206:209], v[116:119], v[16:19]
	s_waitcnt lgkmcnt(8)
	v_mfma_f32_16x16x32_bf16 v[16:19], v[210:213], v[120:123], v[16:19]
	ds_read_b64_tr_b16 v[206:207], v149 offset:448
	ds_read_b64_tr_b16 v[208:209], v149 offset:2560
	ds_read_b64_tr_b16 v[210:211], v149 offset:17344
	ds_read_b64_tr_b16 v[212:213], v149 offset:19456
	v_mul_f32_e32 v14, v150, v14
	v_mul_f32_e32 v15, v151, v15
	v_mul_f32_e32 v12, v152, v12
	v_mul_f32_e32 v13, v153, v13
	s_waitcnt lgkmcnt(10)
	s_nop 0
	v_mfma_f32_16x16x32_bf16 v[12:15], v[214:217], v[116:119], v[12:15]
	s_waitcnt lgkmcnt(8)
	v_mfma_f32_16x16x32_bf16 v[12:15], v[218:221], v[120:123], v[12:15]
	ds_read_b64_tr_b16 v[214:215], v149 offset:480
	ds_read_b64_tr_b16 v[216:217], v149 offset:2592
	ds_read_b64_tr_b16 v[218:219], v149 offset:17376
	ds_read_b64_tr_b16 v[220:221], v149 offset:19488
	v_mul_f32_e32 v10, v150, v10
	v_mul_f32_e32 v11, v151, v11
	v_mul_f32_e32 v8, v152, v8
	v_mul_f32_e32 v9, v153, v9
	s_waitcnt lgkmcnt(10)
	s_nop 0
	v_mfma_f32_16x16x32_bf16 v[8:11], v[222:225], v[116:119], v[8:11]
	s_waitcnt lgkmcnt(8)
; __device__ __forceinline__ u32x2 pack4(f32x4 v) { return (u32x2){pk2(v[0], v[1]), pk2(v[2], v[3])}; }
; #define LDS_BAR() do { asm volatile("s_waitcnt lgkmcnt(0)" ::: "memory"); __builtin_amdgcn_s_barrier(); asm volatile("" ::: "memory"); } while (0)
; #define SB0 __builtin_amdgcn_sched_barrier(0)
; #define SB0 __builtin_amdgcn_sched_barrier(0)
; #define RD_LOAD(m_) do { _Pragma("unroll") for (int ks = 0; ks < 2; ++ks) TR_FRAG(kf[(m_) % 3][ks], Kl, 264, 16 * (m_), ks); } while (0)
; __device__ __forceinline__ void ret_unit(LAS unsigned char* lds, bf16_t* QKV, float* gn, int b, int h, int vs, bool commit, const float* s00p, const float* ss3, bool skel = false) {
;     ...
; #pragma unroll
;           for (int m = 0; m < 16; ++m) { if (m + 2 < 16) RD_LOAD(m + 2);
;               state[m] = state[m] * cd; SB0;
; #pragma unroll
;               for (int ks = 0; ks < 2; ++ks) state[m] = __builtin_amdgcn_mfma_f32_16x16x32_bf16(kf[m % 3][ks], vfrag[ks], state[m], 0, 0, 0);
;               SB0; }
;     ...
;         }
;         }
;     ...
; #pragma unroll
;         for (int n = 0; n < 4; ++n) { const f32x4 o = oacc[n];
;             float s1 = (o[0] + o[1]) + (o[2] + o[3]), s2 = (o[0] * o[0] + o[1] * o[1]) + (o[2] * o[2] + o[3] * o[3]);
;             s1 += __shfl_xor(s1, 16); s1 += __shfl_xor(s1, 32); s2 += __shfl_xor(s2, 16); s2 += __shfl_xor(s2, 32);
;             if (fq == 0) { atomicAdd((float*)(st + (16 * n + fr) * 2), s1); atomicAdd((float*)(st + (16 * n + fr) * 2 + 1), s2); }
;             if (commit) *(u32x2*)(QKV + (trow0 + 16 * n + fr) * RET_QKV + 2048 + 512 * h + 128 * vs + 16 * w + 4 * fq) = pack4(o); }
;         LDS_BAR();
;         if (tid < 128) { if (commit) atomicAdd(gn + ((trow0 + (tid >> 1)) * 4 + h) * 2 + (tid & 1), st[tid]); st[tid] = 0.f; }
	v_mfma_f32_16x16x32_bf16 v[8:11], v[226:229], v[120:123], v[8:11]
	v_mul_f32_e64 v6, v150, v6
	v_mul_f32_e64 v7, v151, v7
	v_mul_f32_e32 v4, v152, v4
	v_mul_f32_e32 v5, v153, v5
	s_waitcnt lgkmcnt(6)
	s_nop 0
	v_mfma_f32_16x16x32_bf16 v[4:7], v[206:209], v[116:119], v[4:7]
	s_waitcnt lgkmcnt(4)
	v_mfma_f32_16x16x32_bf16 v[4:7], v[210:213], v[120:123], v[4:7]
	v_mul_f32_e64 v2, v150, v2
	v_mul_f32_e64 v3, v151, v3
	v_mul_f32_e32 v0, v152, v0
	v_mul_f32_e32 v1, v153, v1
	s_waitcnt lgkmcnt(2)
	s_nop 0
	v_mfma_f32_16x16x32_bf16 v[0:3], v[214:217], v[116:119], v[0:3]
	s_waitcnt lgkmcnt(0)
	v_mfma_f32_16x16x32_bf16 v[0:3], v[218:221], v[120:123], v[0:3]
	v_and_b32_e32 v117, 64, v202
	v_xor_b32_e32 v116, 16, v202
	v_add_u32_e32 v117, 64, v117
	v_cmp_lt_i32_e32 vcc, v116, v117
	v_add_f32_e32 v222, v124, v125
	v_add_f32_e32 v230, v126, v127
	v_cndmask_b32_e32 v116, v202, v116, vcc
	v_lshlrev_b32_e32 v118, 2, v116
	v_xor_b32_e32 v116, 32, v202
	v_cmp_lt_i32_e32 vcc, v116, v117
	v_mul_f32_e32 v226, v124, v124
	v_mul_f32_e32 v231, v126, v126
	v_cndmask_b32_e32 v116, v202, v116, vcc
	v_lshlrev_b32_e32 v119, 2, v116
	v_add_f32_e32 v223, v112, v113
	v_add_f32_e32 v232, v114, v115
	v_fmac_f32_e32 v226, v125, v125
	v_fmac_f32_e32 v231, v127, v127
	v_mul_f32_e32 v227, v112, v112
	v_mul_f32_e32 v233, v114, v114
	v_add_f32_e32 v222, v222, v230
	v_add_f32_e32 v226, v226, v231
	v_fmac_f32_e32 v227, v113, v113
	v_fmac_f32_e32 v233, v115, v115
	v_add_f32_e32 v223, v223, v232
	v_add_f32_e32 v224, v108, v109
	v_add_f32_e32 v230, v110, v111
	v_add_f32_e32 v227, v227, v233
	v_mul_f32_e32 v228, v108, v108
	v_mul_f32_e32 v231, v110, v110
	v_add_f32_e32 v225, v104, v105
	v_add_f32_e32 v232, v106, v107
	v_fmac_f32_e32 v228, v109, v109
	v_fmac_f32_e32 v231, v111, v111
	v_mul_f32_e32 v229, v104, v104
	v_mul_f32_e32 v233, v106, v106
	v_add_f32_e32 v224, v224, v230
	v_add_f32_e32 v228, v228, v231
	v_fmac_f32_e32 v229, v105, v105
	v_fmac_f32_e32 v233, v107, v107
	v_add_f32_e32 v225, v225, v232
	v_add_f32_e32 v229, v229, v233
	v_lshl_add_u64 v[116:117], s[50:51], 0, v[156:157]
	s_nop 1
	v_permlane16_swap_b32_e32 v222, v224
	v_permlane16_swap_b32_e32 v226, v228
	v_permlane16_swap_b32_e32 v223, v225
	v_permlane16_swap_b32_e32 v227, v229
	v_add_f32_e32 v222, v222, v224
	v_add_f32_e32 v226, v226, v228
	v_add_f32_e32 v223, v223, v225
	v_add_f32_e32 v227, v227, v229
	v_cvt_pk_bf16_f32 v124, v124, v125
	v_cvt_pk_bf16_f32 v125, v126, v127
	v_permlane32_swap_b32_e32 v222, v223
	v_permlane32_swap_b32_e32 v226, v227
	v_add_co_u32_e32 v126, vcc, 0xe201000, v116
	v_add_f32_e32 v222, v222, v223
	v_add_f32_e32 v226, v226, v227
	v_addc_co_u32_e32 v127, vcc, 0, v117, vcc
	ds_add_f32 v255, v222
	ds_add_f32 v255, v226 offset:4
	global_store_dwordx2 v[126:127], v[124:125], off
	v_cvt_pk_bf16_f32 v120, v112, v113
	v_cvt_pk_bf16_f32 v121, v114, v115
	v_add_co_u32_e32 v122, vcc, 0xe221000, v116
	s_nop 1
	v_addc_co_u32_e32 v123, vcc, 0, v117, vcc
	global_store_dwordx2 v[122:123], v[120:121], off
	v_cvt_pk_bf16_f32 v112, v108, v109
	v_cvt_pk_bf16_f32 v113, v110, v111
	v_add_co_u32_e32 v114, vcc, 0xe241000, v116
	s_nop 1
	v_addc_co_u32_e32 v115, vcc, 0, v117, vcc
	global_store_dwordx2 v[114:115], v[112:113], off
	v_cvt_pk_bf16_f32 v104, v104, v105
	v_cvt_pk_bf16_f32 v105, v106, v107
	v_add_co_u32_e32 v106, vcc, 0xe261000, v116
	s_nop 1
	v_addc_co_u32_e32 v107, vcc, 0, v117, vcc
	global_store_dwordx2 v[106:107], v[104:105], off
	s_waitcnt lgkmcnt(0)
	s_barrier
	s_and_saveexec_b64 s[64:65], s[4:5]
	s_cbranch_execz .LBB0_1136
	ds_read_b32 v106, v162
	v_lshl_add_u64 v[104:105], s[50:51], 0, v[158:159]
	s_waitcnt lgkmcnt(0)
	global_atomic_add_f32 v[104:105], v106, off
	ds_write_b32 v162, v133
	s_branch .LBB0_1136
